# P5 K-loop: last iteration peeled without the next-unit LDS-DMAs, counted waits re-derived
# baseline (speedup 1.0000x reference)
.Lp5pf_skip:
	ds_read_b128 v[144:147], v139
	ds_read_b128 v[148:151], v139 offset:1024
	ds_read_b128 v[152:155], v139 offset:2048
	ds_read_b128 v[156:159], v139 offset:3072
	ds_read_b128 v[164:167], v140
	ds_read_b128 v[168:171], v140 offset:1024
	ds_read_b128 v[172:175], v140 offset:2048
	ds_read_b128 v[176:179], v140 offset:3072
	s_add_u32 s12, s8, s10
	s_addc_u32 s13, s9, s11
	s_add_u32 s12, s12, 0x2000100
	s_addc_u32 s13, s13, 0
	s_add_u32 s42, s27, s10
	s_addc_u32 s43, s28, s11
	s_cmpk_eq_i32 s10, 0x3f00
	s_cselect_b32 s15, s3, s13
	s_cselect_b32 s14, s2, s12
	s_cselect_b32 s13, s1, s43
	s_cselect_b32 s12, s0, s42
	s_mov_b32 m0, s30
	v_lshl_add_u64 v[160:161], v[134:135], 0, s[10:11]
	ds_read_b128 v[180:183], v141
	ds_read_b128 v[184:187], v141 offset:1024
	ds_read_b128 v[188:191], v141 offset:2048
	ds_read_b128 v[196:199], v141 offset:3072
	ds_read_b128 v[200:203], v141 offset:4096
	ds_read_b128 v[204:207], v141 offset:5120
	ds_read_b128 v[208:211], v141 offset:6144
	ds_read_b128 v[212:215], v141 offset:7168
	global_load_lds_dwordx4 v[160:161], off
	v_lshl_add_u64 v[160:161], v[136:137], 0, s[10:11]
	s_mov_b32 m0, s31
	s_nop 0
	global_load_lds_dwordx4 v[160:161], off
	s_waitcnt vmcnt(8) lgkmcnt(0)
	s_barrier
	v_mfma_f32_16x16x32_bf16 v[126:129], v[144:147], v[180:183], v[126:129]
	v_mfma_f32_16x16x32_bf16 v[122:125], v[152:155], v[180:183], v[122:125]
	v_mfma_f32_16x16x32_bf16 v[110:113], v[144:147], v[188:191], v[110:113]
	v_mfma_f32_16x16x32_bf16 v[106:109], v[152:155], v[188:191], v[106:109]
	v_mfma_f32_16x16x32_bf16 v[94:97], v[144:147], v[200:203], v[94:97]
	v_mfma_f32_16x16x32_bf16 v[90:93], v[152:155], v[200:203], v[90:93]
	v_mfma_f32_16x16x32_bf16 v[78:81], v[144:147], v[208:211], v[78:81]
	v_mfma_f32_16x16x32_bf16 v[74:77], v[152:155], v[208:211], v[74:77]
	v_mfma_f32_16x16x32_bf16 v[126:129], v[148:151], v[184:187], v[126:129]
	v_mfma_f32_16x16x32_bf16 v[122:125], v[156:159], v[184:187], v[122:125]
	v_mfma_f32_16x16x32_bf16 v[110:113], v[148:151], v[196:199], v[110:113]
	v_mfma_f32_16x16x32_bf16 v[106:109], v[156:159], v[196:199], v[106:109]
	v_mfma_f32_16x16x32_bf16 v[94:97], v[148:151], v[204:207], v[94:97]
	v_mfma_f32_16x16x32_bf16 v[90:93], v[156:159], v[204:207], v[90:93]
	v_mfma_f32_16x16x32_bf16 v[78:81], v[148:151], v[212:215], v[78:81]
	v_mfma_f32_16x16x32_bf16 v[74:77], v[156:159], v[212:215], v[74:77]
	v_mfma_f32_16x16x32_bf16 v[118:121], v[164:167], v[180:183], v[118:121]
	v_mfma_f32_16x16x32_bf16 v[114:117], v[172:175], v[180:183], v[114:117]
	v_mfma_f32_16x16x32_bf16 v[102:105], v[164:167], v[188:191], v[102:105]
	v_mfma_f32_16x16x32_bf16 v[98:101], v[172:175], v[188:191], v[98:101]
	v_mfma_f32_16x16x32_bf16 v[86:89], v[164:167], v[200:203], v[86:89]
	v_mfma_f32_16x16x32_bf16 v[82:85], v[172:175], v[200:203], v[82:85]
	v_mfma_f32_16x16x32_bf16 v[70:73], v[164:167], v[208:211], v[70:73]
	v_mfma_f32_16x16x32_bf16 v[66:69], v[172:175], v[208:211], v[66:69]
	v_mfma_f32_16x16x32_bf16 v[118:121], v[168:171], v[184:187], v[118:121]
	v_mfma_f32_16x16x32_bf16 v[114:117], v[176:179], v[184:187], v[114:117]
	v_mfma_f32_16x16x32_bf16 v[102:105], v[168:171], v[196:199], v[102:105]
	v_mfma_f32_16x16x32_bf16 v[98:101], v[176:179], v[196:199], v[98:101]
	v_mfma_f32_16x16x32_bf16 v[86:89], v[168:171], v[204:207], v[86:89]
	v_mfma_f32_16x16x32_bf16 v[82:85], v[176:179], v[204:207], v[82:85]
	v_mfma_f32_16x16x32_bf16 v[70:73], v[168:171], v[212:215], v[70:73]
	v_mfma_f32_16x16x32_bf16 v[66:69], v[176:179], v[212:215], v[66:69]
	s_barrier
	s_mov_b32 m0, s34
	s_add_u32 s42, s12, 0x200000
	s_addc_u32 s43, s13, 0
	ds_read_b128 v[180:183], v141 offset:16384
	ds_read_b128 v[184:187], v141 offset:17408
	ds_read_b128 v[188:191], v141 offset:18432
	ds_read_b128 v[196:199], v141 offset:19456
	ds_read_b128 v[200:203], v141 offset:20480
	ds_read_b128 v[204:207], v141 offset:21504
	ds_read_b128 v[208:211], v141 offset:22528
	ds_read_b128 v[212:215], v141 offset:23552
	global_load_lds_dwordx4 v130, s[12:13]
	s_mov_b32 m0, s35
	s_nop 0
	global_load_lds_dwordx4 v132, s[12:13]
	s_mov_b32 m0, s36
	s_nop 0
	global_load_lds_dwordx4 v130, s[42:43]
	s_mov_b32 m0, s37
	s_nop 0
	global_load_lds_dwordx4 v132, s[42:43]
	s_mov_b32 m0, s20
	s_nop 0
	global_load_lds_dwordx4 v130, s[14:15]
	s_mov_b32 m0, s21
	s_nop 0
	global_load_lds_dwordx4 v132, s[14:15]
	s_waitcnt vmcnt(8) lgkmcnt(0)
	s_barrier
	v_mfma_f32_16x16x32_bf16 v[62:65], v[144:147], v[180:183], v[62:65]
	v_mfma_f32_16x16x32_bf16 v[58:61], v[152:155], v[180:183], v[58:61]
	v_mfma_f32_16x16x32_bf16 v[46:49], v[144:147], v[188:191], v[46:49]
	v_mfma_f32_16x16x32_bf16 v[42:45], v[152:155], v[188:191], v[42:45]
	v_mfma_f32_16x16x32_bf16 v[30:33], v[144:147], v[200:203], v[30:33]
	v_mfma_f32_16x16x32_bf16 v[26:29], v[152:155], v[200:203], v[26:29]
	v_mfma_f32_16x16x32_bf16 v[14:17], v[144:147], v[208:211], v[14:17]
	v_mfma_f32_16x16x32_bf16 v[10:13], v[152:155], v[208:211], v[10:13]
	v_mfma_f32_16x16x32_bf16 v[62:65], v[148:151], v[184:187], v[62:65]
	v_mfma_f32_16x16x32_bf16 v[58:61], v[156:159], v[184:187], v[58:61]
	v_mfma_f32_16x16x32_bf16 v[46:49], v[148:151], v[196:199], v[46:49]
	v_mfma_f32_16x16x32_bf16 v[42:45], v[156:159], v[196:199], v[42:45]
	v_mfma_f32_16x16x32_bf16 v[30:33], v[148:151], v[204:207], v[30:33]
	v_mfma_f32_16x16x32_bf16 v[26:29], v[156:159], v[204:207], v[26:29]
	v_mfma_f32_16x16x32_bf16 v[14:17], v[148:151], v[212:215], v[14:17]
	v_mfma_f32_16x16x32_bf16 v[10:13], v[156:159], v[212:215], v[10:13]
	v_mfma_f32_16x16x32_bf16 v[54:57], v[164:167], v[180:183], v[54:57]
	v_mfma_f32_16x16x32_bf16 v[50:53], v[172:175], v[180:183], v[50:53]
	v_mfma_f32_16x16x32_bf16 v[38:41], v[164:167], v[188:191], v[38:41]
	v_mfma_f32_16x16x32_bf16 v[34:37], v[172:175], v[188:191], v[34:37]
	v_mfma_f32_16x16x32_bf16 v[22:25], v[164:167], v[200:203], v[22:25]
	v_mfma_f32_16x16x32_bf16 v[18:21], v[172:175], v[200:203], v[18:21]
	v_mfma_f32_16x16x32_bf16 v[6:9], v[164:167], v[208:211], v[6:9]
	v_mfma_f32_16x16x32_bf16 v[2:5], v[172:175], v[208:211], v[2:5]
	v_mfma_f32_16x16x32_bf16 v[54:57], v[168:171], v[184:187], v[54:57]
	v_mfma_f32_16x16x32_bf16 v[50:53], v[176:179], v[184:187], v[50:53]
	v_mfma_f32_16x16x32_bf16 v[38:41], v[168:171], v[196:199], v[38:41]
	v_mfma_f32_16x16x32_bf16 v[34:37], v[176:179], v[196:199], v[34:37]
	v_mfma_f32_16x16x32_bf16 v[22:25], v[168:171], v[204:207], v[22:25]
	v_mfma_f32_16x16x32_bf16 v[18:21], v[176:179], v[204:207], v[18:21]
	v_mfma_f32_16x16x32_bf16 v[6:9], v[168:171], v[212:215], v[6:9]
	v_mfma_f32_16x16x32_bf16 v[2:5], v[176:179], v[212:215], v[2:5]
	s_barrier
	ds_read_b128 v[144:147], v142
	ds_read_b128 v[148:151], v142 offset:1024
	ds_read_b128 v[152:155], v142 offset:2048
	ds_read_b128 v[156:159], v142 offset:3072
	ds_read_b128 v[164:167], v143
	ds_read_b128 v[168:171], v143 offset:1024
	ds_read_b128 v[172:175], v143 offset:2048
	ds_read_b128 v[176:179], v143 offset:3072
	s_add_u32 s14, s14, 0x200000
	s_addc_u32 s15, s15, 0
	s_mov_b32 m0, s22
	ds_read_b128 v[180:183], v141 offset:32768
	ds_read_b128 v[184:187], v141 offset:33792
	ds_read_b128 v[188:191], v141 offset:34816
	ds_read_b128 v[196:199], v141 offset:35840
	ds_read_b128 v[200:203], v141 offset:36864
	ds_read_b128 v[204:207], v141 offset:37888
	ds_read_b128 v[208:211], v141 offset:38912
	ds_read_b128 v[212:215], v141 offset:39936
	global_load_lds_dwordx4 v130, s[14:15]
	s_mov_b32 m0, s23
	s_nop 0
	global_load_lds_dwordx4 v132, s[14:15]
	s_waitcnt vmcnt(8) lgkmcnt(0)
	s_barrier
	v_mfma_f32_16x16x32_bf16 v[126:129], v[144:147], v[180:183], v[126:129]
	v_mfma_f32_16x16x32_bf16 v[122:125], v[152:155], v[180:183], v[122:125]
	v_mfma_f32_16x16x32_bf16 v[110:113], v[144:147], v[188:191], v[110:113]
	v_mfma_f32_16x16x32_bf16 v[106:109], v[152:155], v[188:191], v[106:109]
	v_mfma_f32_16x16x32_bf16 v[94:97], v[144:147], v[200:203], v[94:97]
	v_mfma_f32_16x16x32_bf16 v[90:93], v[152:155], v[200:203], v[90:93]
	v_mfma_f32_16x16x32_bf16 v[78:81], v[144:147], v[208:211], v[78:81]
	v_mfma_f32_16x16x32_bf16 v[74:77], v[152:155], v[208:211], v[74:77]
	v_mfma_f32_16x16x32_bf16 v[126:129], v[148:151], v[184:187], v[126:129]
	v_mfma_f32_16x16x32_bf16 v[122:125], v[156:159], v[184:187], v[122:125]
	v_mfma_f32_16x16x32_bf16 v[110:113], v[148:151], v[196:199], v[110:113]
	v_mfma_f32_16x16x32_bf16 v[106:109], v[156:159], v[196:199], v[106:109]
	v_mfma_f32_16x16x32_bf16 v[94:97], v[148:151], v[204:207], v[94:97]
	v_mfma_f32_16x16x32_bf16 v[90:93], v[156:159], v[204:207], v[90:93]
	v_mfma_f32_16x16x32_bf16 v[78:81], v[148:151], v[212:215], v[78:81]
	v_mfma_f32_16x16x32_bf16 v[74:77], v[156:159], v[212:215], v[74:77]
	v_mfma_f32_16x16x32_bf16 v[118:121], v[164:167], v[180:183], v[118:121]
	v_mfma_f32_16x16x32_bf16 v[114:117], v[172:175], v[180:183], v[114:117]
	v_mfma_f32_16x16x32_bf16 v[102:105], v[164:167], v[188:191], v[102:105]
	v_mfma_f32_16x16x32_bf16 v[98:101], v[172:175], v[188:191], v[98:101]
	v_mfma_f32_16x16x32_bf16 v[86:89], v[164:167], v[200:203], v[86:89]
	v_mfma_f32_16x16x32_bf16 v[82:85], v[172:175], v[200:203], v[82:85]
	v_mfma_f32_16x16x32_bf16 v[70:73], v[164:167], v[208:211], v[70:73]
	v_mfma_f32_16x16x32_bf16 v[66:69], v[172:175], v[208:211], v[66:69]
	v_mfma_f32_16x16x32_bf16 v[118:121], v[168:171], v[184:187], v[118:121]
	v_mfma_f32_16x16x32_bf16 v[114:117], v[176:179], v[184:187], v[114:117]
	v_mfma_f32_16x16x32_bf16 v[102:105], v[168:171], v[196:199], v[102:105]
	v_mfma_f32_16x16x32_bf16 v[98:101], v[176:179], v[196:199], v[98:101]
	v_mfma_f32_16x16x32_bf16 v[86:89], v[168:171], v[204:207], v[86:89]
	v_mfma_f32_16x16x32_bf16 v[82:85], v[176:179], v[204:207], v[82:85]
	v_mfma_f32_16x16x32_bf16 v[70:73], v[168:171], v[212:215], v[70:73]
	v_mfma_f32_16x16x32_bf16 v[66:69], v[176:179], v[212:215], v[66:69]
	s_barrier
	s_mov_b32 m0, s38
	s_add_u32 s12, s12, 0x200080
	s_addc_u32 s13, s13, 0
	ds_read_b128 v[180:183], v141 offset:49152
	ds_read_b128 v[184:187], v141 offset:50176
	ds_read_b128 v[188:191], v141 offset:51200
	ds_read_b128 v[196:199], v141 offset:52224
	ds_read_b128 v[200:203], v141 offset:53248
	ds_read_b128 v[204:207], v141 offset:54272
	ds_read_b128 v[208:211], v141 offset:55296
	ds_read_b128 v[212:215], v141 offset:56320
	s_add_u32 s98, s12, 0xffe00000
	s_addc_u32 s99, s13, -1
	global_load_lds_dwordx4 v130, s[98:99]
	s_mov_b32 m0, s39
	s_nop 0
	global_load_lds_dwordx4 v132, s[98:99]
	s_mov_b32 m0, s40
	s_nop 0
	global_load_lds_dwordx4 v130, s[12:13]
	s_mov_b32 m0, s41
	s_nop 0
	global_load_lds_dwordx4 v132, s[12:13]
	s_mov_b32 m0, s25
	s_nop 0
	s_add_u32 s100, s14, 0xffe00080
	s_addc_u32 s101, s15, -1
	global_load_lds_dwordx4 v130, s[100:101]
	s_mov_b32 m0, s26
	s_nop 0
	global_load_lds_dwordx4 v132, s[100:101]
	s_waitcnt vmcnt(8) lgkmcnt(0)
	s_barrier
	v_mfma_f32_16x16x32_bf16 v[62:65], v[144:147], v[180:183], v[62:65]
	v_mfma_f32_16x16x32_bf16 v[58:61], v[152:155], v[180:183], v[58:61]
	v_mfma_f32_16x16x32_bf16 v[46:49], v[144:147], v[188:191], v[46:49]
	v_mfma_f32_16x16x32_bf16 v[42:45], v[152:155], v[188:191], v[42:45]
	v_mfma_f32_16x16x32_bf16 v[30:33], v[144:147], v[200:203], v[30:33]
	v_mfma_f32_16x16x32_bf16 v[26:29], v[152:155], v[200:203], v[26:29]
	v_mfma_f32_16x16x32_bf16 v[14:17], v[144:147], v[208:211], v[14:17]
	v_mfma_f32_16x16x32_bf16 v[10:13], v[152:155], v[208:211], v[10:13]
	v_mfma_f32_16x16x32_bf16 v[62:65], v[148:151], v[184:187], v[62:65]
	v_mfma_f32_16x16x32_bf16 v[58:61], v[156:159], v[184:187], v[58:61]
	v_mfma_f32_16x16x32_bf16 v[46:49], v[148:151], v[196:199], v[46:49]
	v_mfma_f32_16x16x32_bf16 v[42:45], v[156:159], v[196:199], v[42:45]
	v_mfma_f32_16x16x32_bf16 v[30:33], v[148:151], v[204:207], v[30:33]
	v_mfma_f32_16x16x32_bf16 v[26:29], v[156:159], v[204:207], v[26:29]
	v_mfma_f32_16x16x32_bf16 v[14:17], v[148:151], v[212:215], v[14:17]
	v_mfma_f32_16x16x32_bf16 v[10:13], v[156:159], v[212:215], v[10:13]
	v_mfma_f32_16x16x32_bf16 v[54:57], v[164:167], v[180:183], v[54:57]
	v_mfma_f32_16x16x32_bf16 v[50:53], v[172:175], v[180:183], v[50:53]
	v_mfma_f32_16x16x32_bf16 v[38:41], v[164:167], v[188:191], v[38:41]
	v_mfma_f32_16x16x32_bf16 v[34:37], v[172:175], v[188:191], v[34:37]
	v_mfma_f32_16x16x32_bf16 v[22:25], v[164:167], v[200:203], v[22:25]
	v_mfma_f32_16x16x32_bf16 v[18:21], v[172:175], v[200:203], v[18:21]
	v_mfma_f32_16x16x32_bf16 v[6:9], v[164:167], v[208:211], v[6:9]
	v_mfma_f32_16x16x32_bf16 v[2:5], v[172:175], v[208:211], v[2:5]
	v_mfma_f32_16x16x32_bf16 v[54:57], v[168:171], v[184:187], v[54:57]
	v_mfma_f32_16x16x32_bf16 v[50:53], v[176:179], v[184:187], v[50:53]
	v_mfma_f32_16x16x32_bf16 v[38:41], v[168:171], v[196:199], v[38:41]
	v_mfma_f32_16x16x32_bf16 v[34:37], v[176:179], v[196:199], v[34:37]
	v_mfma_f32_16x16x32_bf16 v[22:25], v[168:171], v[204:207], v[22:25]
	v_mfma_f32_16x16x32_bf16 v[18:21], v[176:179], v[204:207], v[18:21]
	v_mfma_f32_16x16x32_bf16 v[6:9], v[168:171], v[212:215], v[6:9]
	v_mfma_f32_16x16x32_bf16 v[2:5], v[176:179], v[212:215], v[2:5]
	s_barrier
	s_add_i32 s29, s29, 2
	s_add_u32 s10, s10, 0x100
	s_addc_u32 s11, s11, 0
	s_cmpk_lt_u32 s29, 0x7c
	s_cbranch_scc1 .LBB0_1031
	ds_read_b128 v[144:147], v139
	ds_read_b128 v[148:151], v139 offset:1024
	ds_read_b128 v[152:155], v139 offset:2048
	ds_read_b128 v[156:159], v139 offset:3072
	ds_read_b128 v[164:167], v140
	ds_read_b128 v[168:171], v140 offset:1024
	ds_read_b128 v[172:175], v140 offset:2048
	ds_read_b128 v[176:179], v140 offset:3072
	s_add_u32 s12, s8, s10
	s_addc_u32 s13, s9, s11
	s_add_u32 s12, s12, 0x2000100
	s_addc_u32 s13, s13, 0
	s_add_u32 s42, s27, s10
	s_addc_u32 s43, s28, s11
	s_cmpk_eq_i32 s10, 0x3f00
	s_cselect_b32 s15, s3, s13
	s_cselect_b32 s14, s2, s12
	s_cselect_b32 s13, s1, s43
	s_cselect_b32 s12, s0, s42
	s_mov_b32 m0, s30
	v_lshl_add_u64 v[160:161], v[134:135], 0, s[10:11]
	ds_read_b128 v[180:183], v141
	ds_read_b128 v[184:187], v141 offset:1024
	ds_read_b128 v[188:191], v141 offset:2048
	ds_read_b128 v[196:199], v141 offset:3072
	ds_read_b128 v[200:203], v141 offset:4096
	ds_read_b128 v[204:207], v141 offset:5120
	ds_read_b128 v[208:211], v141 offset:6144
	ds_read_b128 v[212:215], v141 offset:7168
	global_load_lds_dwordx4 v[160:161], off
	v_lshl_add_u64 v[160:161], v[136:137], 0, s[10:11]
	s_mov_b32 m0, s31
	s_nop 0
	global_load_lds_dwordx4 v[160:161], off
	s_waitcnt vmcnt(8) lgkmcnt(0)
	s_barrier
	v_mfma_f32_16x16x32_bf16 v[126:129], v[144:147], v[180:183], v[126:129]
	v_mfma_f32_16x16x32_bf16 v[122:125], v[152:155], v[180:183], v[122:125]
	v_mfma_f32_16x16x32_bf16 v[110:113], v[144:147], v[188:191], v[110:113]
	v_mfma_f32_16x16x32_bf16 v[106:109], v[152:155], v[188:191], v[106:109]
	v_mfma_f32_16x16x32_bf16 v[94:97], v[144:147], v[200:203], v[94:97]
	v_mfma_f32_16x16x32_bf16 v[90:93], v[152:155], v[200:203], v[90:93]
	v_mfma_f32_16x16x32_bf16 v[78:81], v[144:147], v[208:211], v[78:81]
	v_mfma_f32_16x16x32_bf16 v[74:77], v[152:155], v[208:211], v[74:77]
	v_mfma_f32_16x16x32_bf16 v[126:129], v[148:151], v[184:187], v[126:129]
	v_mfma_f32_16x16x32_bf16 v[122:125], v[156:159], v[184:187], v[122:125]
	v_mfma_f32_16x16x32_bf16 v[110:113], v[148:151], v[196:199], v[110:113]
	v_mfma_f32_16x16x32_bf16 v[106:109], v[156:159], v[196:199], v[106:109]
	v_mfma_f32_16x16x32_bf16 v[94:97], v[148:151], v[204:207], v[94:97]
	v_mfma_f32_16x16x32_bf16 v[90:93], v[156:159], v[204:207], v[90:93]
	v_mfma_f32_16x16x32_bf16 v[78:81], v[148:151], v[212:215], v[78:81]
	v_mfma_f32_16x16x32_bf16 v[74:77], v[156:159], v[212:215], v[74:77]
	v_mfma_f32_16x16x32_bf16 v[118:121], v[164:167], v[180:183], v[118:121]
	v_mfma_f32_16x16x32_bf16 v[114:117], v[172:175], v[180:183], v[114:117]
	v_mfma_f32_16x16x32_bf16 v[102:105], v[164:167], v[188:191], v[102:105]
	v_mfma_f32_16x16x32_bf16 v[98:101], v[172:175], v[188:191], v[98:101]
	v_mfma_f32_16x16x32_bf16 v[86:89], v[164:167], v[200:203], v[86:89]
	v_mfma_f32_16x16x32_bf16 v[82:85], v[172:175], v[200:203], v[82:85]
	v_mfma_f32_16x16x32_bf16 v[70:73], v[164:167], v[208:211], v[70:73]
	v_mfma_f32_16x16x32_bf16 v[66:69], v[172:175], v[208:211], v[66:69]
	v_mfma_f32_16x16x32_bf16 v[118:121], v[168:171], v[184:187], v[118:121]
	v_mfma_f32_16x16x32_bf16 v[114:117], v[176:179], v[184:187], v[114:117]
	v_mfma_f32_16x16x32_bf16 v[102:105], v[168:171], v[196:199], v[102:105]
	v_mfma_f32_16x16x32_bf16 v[98:101], v[176:179], v[196:199], v[98:101]
	v_mfma_f32_16x16x32_bf16 v[86:89], v[168:171], v[204:207], v[86:89]
	v_mfma_f32_16x16x32_bf16 v[82:85], v[176:179], v[204:207], v[82:85]
	v_mfma_f32_16x16x32_bf16 v[70:73], v[168:171], v[212:215], v[70:73]
	v_mfma_f32_16x16x32_bf16 v[66:69], v[176:179], v[212:215], v[66:69]
	s_barrier
	s_add_u32 s42, s12, 0x200000
	s_addc_u32 s43, s13, 0
	ds_read_b128 v[180:183], v141 offset:16384
	ds_read_b128 v[184:187], v141 offset:17408
	ds_read_b128 v[188:191], v141 offset:18432
	ds_read_b128 v[196:199], v141 offset:19456
	ds_read_b128 v[200:203], v141 offset:20480
	ds_read_b128 v[204:207], v141 offset:21504
	ds_read_b128 v[208:211], v141 offset:22528
	ds_read_b128 v[212:215], v141 offset:23552
	s_waitcnt vmcnt(2) lgkmcnt(0)
	s_barrier
	v_mfma_f32_16x16x32_bf16 v[62:65], v[144:147], v[180:183], v[62:65]
	v_mfma_f32_16x16x32_bf16 v[58:61], v[152:155], v[180:183], v[58:61]
	v_mfma_f32_16x16x32_bf16 v[46:49], v[144:147], v[188:191], v[46:49]
	v_mfma_f32_16x16x32_bf16 v[42:45], v[152:155], v[188:191], v[42:45]
	v_mfma_f32_16x16x32_bf16 v[30:33], v[144:147], v[200:203], v[30:33]
	v_mfma_f32_16x16x32_bf16 v[26:29], v[152:155], v[200:203], v[26:29]
	v_mfma_f32_16x16x32_bf16 v[14:17], v[144:147], v[208:211], v[14:17]
	v_mfma_f32_16x16x32_bf16 v[10:13], v[152:155], v[208:211], v[10:13]
	v_mfma_f32_16x16x32_bf16 v[62:65], v[148:151], v[184:187], v[62:65]
	v_mfma_f32_16x16x32_bf16 v[58:61], v[156:159], v[184:187], v[58:61]
	v_mfma_f32_16x16x32_bf16 v[46:49], v[148:151], v[196:199], v[46:49]
	v_mfma_f32_16x16x32_bf16 v[42:45], v[156:159], v[196:199], v[42:45]
	v_mfma_f32_16x16x32_bf16 v[30:33], v[148:151], v[204:207], v[30:33]
	v_mfma_f32_16x16x32_bf16 v[26:29], v[156:159], v[204:207], v[26:29]
	v_mfma_f32_16x16x32_bf16 v[14:17], v[148:151], v[212:215], v[14:17]
	v_mfma_f32_16x16x32_bf16 v[10:13], v[156:159], v[212:215], v[10:13]
	v_mfma_f32_16x16x32_bf16 v[54:57], v[164:167], v[180:183], v[54:57]
	v_mfma_f32_16x16x32_bf16 v[50:53], v[172:175], v[180:183], v[50:53]
	v_mfma_f32_16x16x32_bf16 v[38:41], v[164:167], v[188:191], v[38:41]
	v_mfma_f32_16x16x32_bf16 v[34:37], v[172:175], v[188:191], v[34:37]
	v_mfma_f32_16x16x32_bf16 v[22:25], v[164:167], v[200:203], v[22:25]
	v_mfma_f32_16x16x32_bf16 v[18:21], v[172:175], v[200:203], v[18:21]
	v_mfma_f32_16x16x32_bf16 v[6:9], v[164:167], v[208:211], v[6:9]
	v_mfma_f32_16x16x32_bf16 v[2:5], v[172:175], v[208:211], v[2:5]
	v_mfma_f32_16x16x32_bf16 v[54:57], v[168:171], v[184:187], v[54:57]
	v_mfma_f32_16x16x32_bf16 v[50:53], v[176:179], v[184:187], v[50:53]
	v_mfma_f32_16x16x32_bf16 v[38:41], v[168:171], v[196:199], v[38:41]
	v_mfma_f32_16x16x32_bf16 v[34:37], v[176:179], v[196:199], v[34:37]
	v_mfma_f32_16x16x32_bf16 v[22:25], v[168:171], v[204:207], v[22:25]
	v_mfma_f32_16x16x32_bf16 v[18:21], v[176:179], v[204:207], v[18:21]
	v_mfma_f32_16x16x32_bf16 v[6:9], v[168:171], v[212:215], v[6:9]
	v_mfma_f32_16x16x32_bf16 v[2:5], v[176:179], v[212:215], v[2:5]
	s_barrier
	ds_read_b128 v[144:147], v142
	ds_read_b128 v[148:151], v142 offset:1024
	ds_read_b128 v[152:155], v142 offset:2048
	ds_read_b128 v[156:159], v142 offset:3072
	ds_read_b128 v[164:167], v143
	ds_read_b128 v[168:171], v143 offset:1024
	ds_read_b128 v[172:175], v143 offset:2048
	ds_read_b128 v[176:179], v143 offset:3072
	s_add_u32 s14, s14, 0x200000
	s_addc_u32 s15, s15, 0
	ds_read_b128 v[180:183], v141 offset:32768
	ds_read_b128 v[184:187], v141 offset:33792
	ds_read_b128 v[188:191], v141 offset:34816
	ds_read_b128 v[196:199], v141 offset:35840
	ds_read_b128 v[200:203], v141 offset:36864
	ds_read_b128 v[204:207], v141 offset:37888
	ds_read_b128 v[208:211], v141 offset:38912
	ds_read_b128 v[212:215], v141 offset:39936
	s_waitcnt vmcnt(0) lgkmcnt(0)
	s_barrier
	v_mfma_f32_16x16x32_bf16 v[126:129], v[144:147], v[180:183], v[126:129]
	v_mfma_f32_16x16x32_bf16 v[122:125], v[152:155], v[180:183], v[122:125]
	v_mfma_f32_16x16x32_bf16 v[110:113], v[144:147], v[188:191], v[110:113]
	v_mfma_f32_16x16x32_bf16 v[106:109], v[152:155], v[188:191], v[106:109]
	v_mfma_f32_16x16x32_bf16 v[94:97], v[144:147], v[200:203], v[94:97]
	v_mfma_f32_16x16x32_bf16 v[90:93], v[152:155], v[200:203], v[90:93]
	v_mfma_f32_16x16x32_bf16 v[78:81], v[144:147], v[208:211], v[78:81]
	v_mfma_f32_16x16x32_bf16 v[74:77], v[152:155], v[208:211], v[74:77]
	v_mfma_f32_16x16x32_bf16 v[126:129], v[148:151], v[184:187], v[126:129]
	v_mfma_f32_16x16x32_bf16 v[122:125], v[156:159], v[184:187], v[122:125]
	v_mfma_f32_16x16x32_bf16 v[110:113], v[148:151], v[196:199], v[110:113]
	v_mfma_f32_16x16x32_bf16 v[106:109], v[156:159], v[196:199], v[106:109]
	v_mfma_f32_16x16x32_bf16 v[94:97], v[148:151], v[204:207], v[94:97]
	v_mfma_f32_16x16x32_bf16 v[90:93], v[156:159], v[204:207], v[90:93]
	v_mfma_f32_16x16x32_bf16 v[78:81], v[148:151], v[212:215], v[78:81]
	v_mfma_f32_16x16x32_bf16 v[74:77], v[156:159], v[212:215], v[74:77]
	v_mfma_f32_16x16x32_bf16 v[118:121], v[164:167], v[180:183], v[118:121]
	v_mfma_f32_16x16x32_bf16 v[114:117], v[172:175], v[180:183], v[114:117]
	v_mfma_f32_16x16x32_bf16 v[102:105], v[164:167], v[188:191], v[102:105]
	v_mfma_f32_16x16x32_bf16 v[98:101], v[172:175], v[188:191], v[98:101]
	v_mfma_f32_16x16x32_bf16 v[86:89], v[164:167], v[200:203], v[86:89]
	v_mfma_f32_16x16x32_bf16 v[82:85], v[172:175], v[200:203], v[82:85]
	v_mfma_f32_16x16x32_bf16 v[70:73], v[164:167], v[208:211], v[70:73]
	v_mfma_f32_16x16x32_bf16 v[66:69], v[172:175], v[208:211], v[66:69]
	v_mfma_f32_16x16x32_bf16 v[118:121], v[168:171], v[184:187], v[118:121]
	v_mfma_f32_16x16x32_bf16 v[114:117], v[176:179], v[184:187], v[114:117]
	v_mfma_f32_16x16x32_bf16 v[102:105], v[168:171], v[196:199], v[102:105]
	v_mfma_f32_16x16x32_bf16 v[98:101], v[176:179], v[196:199], v[98:101]
	v_mfma_f32_16x16x32_bf16 v[86:89], v[168:171], v[204:207], v[86:89]
	v_mfma_f32_16x16x32_bf16 v[82:85], v[176:179], v[204:207], v[82:85]
	v_mfma_f32_16x16x32_bf16 v[70:73], v[168:171], v[212:215], v[70:73]
	v_mfma_f32_16x16x32_bf16 v[66:69], v[176:179], v[212:215], v[66:69]
	s_barrier
	s_add_u32 s12, s12, 0x200080
	s_addc_u32 s13, s13, 0
	ds_read_b128 v[180:183], v141 offset:49152
	ds_read_b128 v[184:187], v141 offset:50176
	ds_read_b128 v[188:191], v141 offset:51200
	ds_read_b128 v[196:199], v141 offset:52224
	ds_read_b128 v[200:203], v141 offset:53248
	ds_read_b128 v[204:207], v141 offset:54272
	ds_read_b128 v[208:211], v141 offset:55296
	ds_read_b128 v[212:215], v141 offset:56320
	s_add_u32 s98, s12, 0xffe00000
	s_addc_u32 s99, s13, -1
	s_add_u32 s100, s14, 0xffe00080
	s_addc_u32 s101, s15, -1
	s_waitcnt lgkmcnt(0)
	s_barrier
	v_mfma_f32_16x16x32_bf16 v[62:65], v[144:147], v[180:183], v[62:65]
	v_mfma_f32_16x16x32_bf16 v[58:61], v[152:155], v[180:183], v[58:61]
	v_mfma_f32_16x16x32_bf16 v[46:49], v[144:147], v[188:191], v[46:49]
	v_mfma_f32_16x16x32_bf16 v[42:45], v[152:155], v[188:191], v[42:45]
	v_mfma_f32_16x16x32_bf16 v[30:33], v[144:147], v[200:203], v[30:33]
	v_mfma_f32_16x16x32_bf16 v[26:29], v[152:155], v[200:203], v[26:29]
	v_mfma_f32_16x16x32_bf16 v[14:17], v[144:147], v[208:211], v[14:17]
	v_mfma_f32_16x16x32_bf16 v[10:13], v[152:155], v[208:211], v[10:13]
	v_mfma_f32_16x16x32_bf16 v[62:65], v[148:151], v[184:187], v[62:65]
	v_mfma_f32_16x16x32_bf16 v[58:61], v[156:159], v[184:187], v[58:61]
	v_mfma_f32_16x16x32_bf16 v[46:49], v[148:151], v[196:199], v[46:49]
	v_mfma_f32_16x16x32_bf16 v[42:45], v[156:159], v[196:199], v[42:45]
	v_mfma_f32_16x16x32_bf16 v[30:33], v[148:151], v[204:207], v[30:33]
	v_mfma_f32_16x16x32_bf16 v[26:29], v[156:159], v[204:207], v[26:29]
	v_mfma_f32_16x16x32_bf16 v[14:17], v[148:151], v[212:215], v[14:17]
	v_mfma_f32_16x16x32_bf16 v[10:13], v[156:159], v[212:215], v[10:13]
	v_mfma_f32_16x16x32_bf16 v[54:57], v[164:167], v[180:183], v[54:57]
	v_mfma_f32_16x16x32_bf16 v[50:53], v[172:175], v[180:183], v[50:53]
	v_mfma_f32_16x16x32_bf16 v[38:41], v[164:167], v[188:191], v[38:41]
	v_mfma_f32_16x16x32_bf16 v[34:37], v[172:175], v[188:191], v[34:37]
	v_mfma_f32_16x16x32_bf16 v[22:25], v[164:167], v[200:203], v[22:25]
	v_mfma_f32_16x16x32_bf16 v[18:21], v[172:175], v[200:203], v[18:21]
	v_mfma_f32_16x16x32_bf16 v[6:9], v[164:167], v[208:211], v[6:9]
	v_mfma_f32_16x16x32_bf16 v[2:5], v[172:175], v[208:211], v[2:5]
	v_mfma_f32_16x16x32_bf16 v[54:57], v[168:171], v[184:187], v[54:57]
	v_mfma_f32_16x16x32_bf16 v[50:53], v[176:179], v[184:187], v[50:53]
	v_mfma_f32_16x16x32_bf16 v[38:41], v[168:171], v[196:199], v[38:41]
	v_mfma_f32_16x16x32_bf16 v[34:37], v[176:179], v[196:199], v[34:37]
	v_mfma_f32_16x16x32_bf16 v[22:25], v[168:171], v[204:207], v[22:25]
	v_mfma_f32_16x16x32_bf16 v[18:21], v[176:179], v[204:207], v[18:21]
	v_mfma_f32_16x16x32_bf16 v[6:9], v[168:171], v[212:215], v[6:9]
	v_mfma_f32_16x16x32_bf16 v[2:5], v[176:179], v[212:215], v[2:5]
	s_barrier
	s_waitcnt vmcnt(0)
	s_cmpk_gt_u32 s19, 0xff
	s_cbranch_scc1 .LBB0_1034
	s_barrier
